# v004 + rewritten GLA gating pass (batched LDS reads, packed math), packed fma at LO-select softmax sites, pre-norm modulation loads issued together
# speedup vs baseline: 1.0013x; 1.0013x over previous
.LBB0_226:
	s_mul_i32 s0, s88, 9
	s_waitcnt vmcnt(3)
	v_add_u32_e32 v8, s0, v55
	v_mov_b64_e32 v[6:7], s[14:15]
	s_waitcnt vmcnt(1)
	v_mad_i64_i32 v[14:15], s[4:5], v8, s95, v[6:7]
	s_waitcnt vmcnt(0)
	v_lshl_add_u64 v[18:19], v[14:15], 0, s[52:53]
	v_lshl_add_u64 v[10:11], v[18:19], 0, v[0:1]
	global_load_dwordx4 v[6:9], v[40:41], off
	v_lshl_add_u64 v[20:21], v[14:15], 0, v[0:1]
	global_load_dwordx4 v[10:13], v[10:11], off
	v_mov_b32_e32 v58, v31
	global_load_dwordx4 v[14:17], v[20:21], off
	v_mov_b32_e32 v47, v1
	v_mov_b32_e32 v49, v1
	v_mov_b32_e32 v51, v1
	v_lshl_add_u64 v[120:121], v[18:19], 0, v[46:47]
	v_lshl_add_u64 v[122:123], v[18:19], 0, v[48:49]
	v_lshl_add_u64 v[124:125], v[18:19], 0, v[50:51]
	global_load_dwordx4 v[84:87], v[40:41], off offset:1024
	global_load_dwordx4 v[108:111], v[120:121], off
	global_load_dwordx4 v[96:99], v[20:21], off offset:1024
	global_load_dwordx4 v[88:91], v[40:41], off offset:2048
	global_load_dwordx4 v[112:115], v[122:123], off
	global_load_dwordx4 v[100:103], v[20:21], off offset:2048
	global_load_dwordx4 v[92:95], v[40:41], off offset:3072
	global_load_dwordx4 v[116:119], v[124:125], off
	global_load_dwordx4 v[104:107], v[20:21], off offset:3072
	v_mov_b32_e32 v59, v27
	v_mov_b32_e32 v56, v30
	v_mov_b32_e32 v57, v26
	v_pk_mul_f32 v[58:59], v[58:59], v[58:59]
	v_mov_b32_e32 v60, v23
	v_pk_fma_f32 v[56:57], v[56:57], v[56:57], v[58:59]
	v_mov_b32_e32 v58, v32
	v_mov_b32_e32 v59, v28
	v_pk_fma_f32 v[56:57], v[58:59], v[58:59], v[56:57]
	v_mov_b32_e32 v58, v33
	v_mov_b32_e32 v59, v29
	v_mov_b32_e32 v61, v3
	v_pk_fma_f32 v[56:57], v[58:59], v[58:59], v[56:57]
	v_mov_b32_e32 v58, v22
	v_mov_b32_e32 v59, v2
	v_pk_mul_f32 v[60:61], v[60:61], v[60:61]
	v_add_f32_e32 v0, v56, v57
	v_pk_fma_f32 v[58:59], v[58:59], v[58:59], v[60:61]
	v_mov_b32_e32 v60, v24
	v_mov_b32_e32 v61, v4
	v_pk_fma_f32 v[58:59], v[60:61], v[60:61], v[58:59]
	v_mov_b32_e32 v60, v25
	v_mov_b32_e32 v61, v5
	v_pk_fma_f32 v[58:59], v[60:61], v[60:61], v[58:59]
	v_lshl_add_u64 v[52:53], v[44:45], 0, v[52:53]
	v_add_f32_e32 v0, v0, v58
	v_add_f32_e32 v0, v0, v59
	ds_swizzle_b32 v35, v0 offset:swizzle(SWAP,1)
	v_mov_b32_e32 v47, v1
	v_lshl_add_u64 v[56:57], v[18:19], 0, v[46:47]
	v_mov_b32_e32 v49, v1
	v_mov_b32_e32 v51, v1
	s_waitcnt lgkmcnt(0)
	v_add_f32_e32 v0, v0, v35
	ds_swizzle_b32 v35, v0 offset:swizzle(SWAP,2)
	v_add_u32_e32 v34, s24, v34
	s_movk_i32 s0, 0x43ff
	s_waitcnt lgkmcnt(0)
	v_add_f32_e32 v0, v0, v35
	ds_swizzle_b32 v35, v0 offset:swizzle(SWAP,4)
	s_waitcnt lgkmcnt(0)
	v_add_f32_e32 v0, v0, v35
	ds_swizzle_b32 v35, v0 offset:swizzle(SWAP,8)
	s_waitcnt lgkmcnt(0)
	v_add_f32_e32 v0, v0, v35
	ds_swizzle_b32 v35, v0 offset:swizzle(SWAP,16)
	s_waitcnt lgkmcnt(0)
	v_add_f32_e32 v0, v0, v35
	ds_bpermute_b32 v35, v37, v0
	s_waitcnt lgkmcnt(0)
	v_add_f32_e32 v0, v0, v35
	v_fmamk_f32 v0, v0, 0x3a800000, v174
	v_mul_f32_e32 v35, 0x4b800000, v0
	v_cmp_gt_f32_e32 vcc, s48, v0
	s_waitcnt vmcnt(10)
	v_pk_add_f32 v[10:11], v[10:11], 1.0 op_sel_hi:[1,0]
	v_cndmask_b32_e32 v0, v0, v35, vcc
	v_rsq_f32_e32 v0, v0
	v_pk_add_f32 v[12:13], v[12:13], 1.0 op_sel_hi:[1,0]
	v_mul_f32_e32 v35, 0x45800000, v0
	v_cndmask_b32_e32 v0, v0, v35, vcc
	v_pk_mul_f32 v[30:31], v[30:31], v[0:1] op_sel_hi:[1,0]
	v_pk_mul_f32 v[32:33], v[32:33], v[0:1] op_sel_hi:[1,0]
	v_pk_mul_f32 v[6:7], v[6:7], v[30:31]
	v_pk_mul_f32 v[8:9], v[8:9], v[32:33]
	s_waitcnt vmcnt(9)
	v_pk_fma_f32 v[6:7], v[10:11], v[6:7], v[14:15]
	v_pk_fma_f32 v[8:9], v[12:13], v[8:9], v[16:17]
	v_cvt_pk_bf16_f32 v6, v6, v7
	v_cvt_pk_bf16_f32 v7, v8, v9
	global_store_dwordx2 v[52:53], v[6:7], off
	v_pk_mul_f32 v[26:27], v[26:27], v[0:1] op_sel_hi:[1,0]
	v_pk_mul_f32 v[28:29], v[28:29], v[0:1] op_sel_hi:[1,0]
	v_pk_mul_f32 v[22:23], v[22:23], v[0:1] op_sel_hi:[1,0]
	v_pk_mul_f32 v[24:25], v[24:25], v[0:1] op_sel_hi:[1,0]
	v_pk_mul_f32 v[2:3], v[2:3], v[0:1] op_sel_hi:[1,0]
	v_pk_mul_f32 v[4:5], v[4:5], v[0:1] op_sel_hi:[1,0]
	v_cmp_lt_i32_e32 vcc, s0, v34
	s_or_b64 s[6:7], vcc, s[6:7]
	s_waitcnt vmcnt(7)
	v_pk_mul_f32 v[84:85], v[26:27], v[84:85]
	v_pk_add_f32 v[108:109], v[108:109], 1.0 op_sel_hi:[1,0]
	v_pk_mul_f32 v[86:87], v[28:29], v[86:87]
	v_pk_add_f32 v[110:111], v[110:111], 1.0 op_sel_hi:[1,0]
	v_pk_fma_f32 v[84:85], v[108:109], v[84:85], v[96:97]
	v_pk_fma_f32 v[86:87], v[110:111], v[86:87], v[98:99]
	v_cvt_pk_bf16_f32 v84, v84, v85
	v_cvt_pk_bf16_f32 v85, v86, v87
	global_store_dwordx2 v[52:53], v[84:85], off offset:512
	s_waitcnt vmcnt(5)
	v_pk_mul_f32 v[88:89], v[22:23], v[88:89]
	v_pk_add_f32 v[112:113], v[112:113], 1.0 op_sel_hi:[1,0]
	v_pk_mul_f32 v[90:91], v[24:25], v[90:91]
	v_pk_add_f32 v[114:115], v[114:115], 1.0 op_sel_hi:[1,0]
	v_pk_fma_f32 v[88:89], v[112:113], v[88:89], v[100:101]
	v_pk_fma_f32 v[90:91], v[114:115], v[90:91], v[102:103]
	v_cvt_pk_bf16_f32 v88, v88, v89
	v_cvt_pk_bf16_f32 v89, v90, v91
	global_store_dwordx2 v[52:53], v[88:89], off offset:1024
	s_waitcnt vmcnt(3)
	v_pk_mul_f32 v[2:3], v[2:3], v[92:93]
	v_pk_add_f32 v[116:117], v[116:117], 1.0 op_sel_hi:[1,0]
	v_pk_mul_f32 v[4:5], v[4:5], v[94:95]
	v_pk_add_f32 v[118:119], v[118:119], 1.0 op_sel_hi:[1,0]
	v_pk_fma_f32 v[2:3], v[116:117], v[2:3], v[104:105]
	v_pk_fma_f32 v[4:5], v[118:119], v[4:5], v[106:107]
	v_cvt_pk_bf16_f32 v2, v2, v3
	v_cvt_pk_bf16_f32 v3, v4, v5
	global_store_dwordx2 v[52:53], v[2:3], off offset:1536
	s_andn2_b64 exec, exec, s[6:7]
	s_cbranch_execz .LBB0_235

.LBB0_464:
	v_ashrrev_i32_e32 v91, 4, v89
	v_xor_b32_e32 v74, v91, v89
	v_lshlrev_b32_e32 v0, 8, v91
	v_lshlrev_b32_e32 v74, 4, v74
	v_and_or_b32 v0, v74, s87, v0
	v_add_u32_e32 v0, 0, v0
	v_lshlrev_b32_e32 v84, 4, v89
	s_waitcnt lgkmcnt(0)
	s_barrier
	s_waitcnt vmcnt(12)
	ds_write_b128 v0, v[2:5]
	s_waitcnt vmcnt(11)
	ds_write_b128 v0, v[6:9] offset:16384
	s_waitcnt vmcnt(10)
	ds_write_b128 v0, v[10:13] offset:4096
	s_waitcnt vmcnt(9)
	ds_write_b128 v0, v[14:17] offset:20480
	s_waitcnt vmcnt(8)
	ds_write_b128 v0, v[18:21] offset:8192
	s_waitcnt vmcnt(7)
	ds_write_b128 v0, v[22:25] offset:24576
	s_waitcnt vmcnt(6)
	ds_write_b128 v0, v[30:33] offset:12288
	s_waitcnt vmcnt(5)
	ds_write_b128 v0, v[34:37] offset:28672
	v_ashrrev_i32_e32 v85, 31, v84
	v_add_u32_e32 v0, 0, v84
	v_cmp_gt_i32_e64 s[6:7], 32, v89
	s_waitcnt vmcnt(3)
	ds_write_b128 v0, v[58:61] offset:32768
	s_waitcnt vmcnt(2)
	ds_write_b128 v0, v[62:65] offset:36864
	s_waitcnt vmcnt(1)
	ds_write_b128 v0, v[66:69] offset:40960
	s_waitcnt vmcnt(0)
	ds_write_b128 v0, v[70:73] offset:45056
	s_and_saveexec_b64 s[16:17], s[6:7]
	v_add_u32_e32 v0, 0, v84
	v_add_u32_e32 v0, 0x13000, v0
	ds_write_b128 v0, v[26:29]
	s_or_b64 exec, exec, s[16:17]
	v_lshlrev_b32_e32 v75, 3, v89
	v_ashrrev_i32_e32 v90, 2, v89
	v_and_b32_e32 v83, 24, v75
	v_ashrrev_i32_e32 v75, 5, v89
	v_lshlrev_b32_e32 v82, 2, v89
	v_lshlrev_b32_e32 v76, 1, v90
	v_bitop3_b32 v78, v82, v75, 4 bitop3:0x6c
	v_and_b32_e32 v76, 14, v76
	v_lshlrev_b32_e32 v77, 7, v83
	v_lshl_add_u32 v78, v78, 4, 0
	v_add3_u32 v77, v78, v77, v76
	ds_write_b16 v77, v54 offset:49152
	ds_write_b16_d16_hi v77, v54 offset:49280
	v_or_b32_e32 v77, 2, v83
	v_lshlrev_b32_e32 v78, 7, v77
	v_lshrrev_b32_e32 v77, 1, v77
	v_bitop3_b32 v77, v77, v75, 5 bitop3:0x6c
	v_lshl_add_u32 v77, v77, 4, 0
	v_add3_u32 v77, v77, v78, v76
	ds_write_b16 v77, v55 offset:49152
	ds_write_b16_d16_hi v77, v55 offset:49280
	v_or_b32_e32 v77, 4, v83
	v_lshlrev_b32_e32 v78, 7, v77
	v_lshrrev_b32_e32 v77, 1, v77
	v_bitop3_b32 v77, v77, v75, 6 bitop3:0x6c
	v_lshl_add_u32 v77, v77, 4, 0
	v_add3_u32 v77, v77, v78, v76
	ds_write_b16 v77, v56 offset:49152
	ds_write_b16_d16_hi v77, v56 offset:49280
	v_or_b32_e32 v77, 6, v83
	v_lshlrev_b32_e32 v78, 7, v77
	v_lshrrev_b32_e32 v77, 1, v77
	v_bitop3_b32 v75, v77, v75, 7 bitop3:0x6c
	v_lshl_add_u32 v75, v75, 4, 0
	v_and_b32_e32 v0, 0x7f, v89
	v_add3_u32 v75, v75, v78, v76
	v_ashrrev_i32_e32 v74, 7, v89
	ds_write_b16 v75, v57 offset:49152
	ds_write_b16_d16_hi v75, v57 offset:49280
	v_lshl_add_u32 v75, v0, 2, 0
	v_add_u32_e32 v79, 0x13000, v75
	v_lshlrev_b32_e32 v92, 2, v74
	v_lshrrev_b32_e32 v75, 1, v89
	v_lshl_add_u32 v93, v0, 7, 0
	v_lshlrev_b32_e32 v0, 13, v74
	v_bitop3_b32 v74, v92, v75, 7 bitop3:0x78
	v_lshlrev_b32_e32 v81, 1, v89
	v_lshl_add_u32 v78, v74, 4, v93
	s_waitcnt lgkmcnt(0)
	s_barrier
	v_lshlrev_b32_e32 v74, 1, v89
	v_lshrrev_b32_e32 v75, 7, v89
	v_and_b32_e32 v74, 0xfe, v74
	v_lshl_or_b32 v76, v75, 13, v74
	v_and_b32_e32 v74, 0x7f, v89
	v_lshlrev_b32_e32 v77, 7, v74
	v_lshl_add_u32 v75, v74, 2, 0
	v_add_u32_e32 v75, 0x13000, v75
	v_bfe_u32 v88, v89, 1, 3
	ds_read_b32 v80, v75
	v_xor_b32_e32 v74, v92, v88
	v_lshl_add_u32 v34, v74, 4, v77
	ds_read_b128 v[18:21], v34 offset:32768
	v_or_b32_e32 v74, 1, v92
	v_xor_b32_e32 v74, v74, v88
	v_lshl_add_u32 v35, v74, 4, v77
	ds_read_b128 v[22:25], v35 offset:32768
	v_or_b32_e32 v74, 2, v92
	v_xor_b32_e32 v74, v74, v88
	v_lshl_add_u32 v36, v74, 4, v77
	ds_read_b128 v[26:29], v36 offset:32768
	v_or_b32_e32 v74, 3, v92
	v_xor_b32_e32 v74, v74, v88
	v_lshl_add_u32 v37, v74, 4, v77
	ds_read_b128 v[30:33], v37 offset:32768
	v_mov_b32_e32 v2, v76
	v_xor_b32_e32 v3, 0x10, v76
	v_xor_b32_e32 v4, 0x20, v76
	v_xor_b32_e32 v5, 0x30, v76
	v_xor_b32_e32 v6, 0x40, v76
	v_xor_b32_e32 v7, 0x50, v76
	v_xor_b32_e32 v8, 0x60, v76
	v_xor_b32_e32 v9, 0x70, v76
	v_xor_b32_e32 v10, 0x80, v76
	v_xor_b32_e32 v11, 0x90, v76
	v_xor_b32_e32 v12, 0xa0, v76
	v_xor_b32_e32 v13, 0xb0, v76
	v_xor_b32_e32 v14, 0xc0, v76
	v_xor_b32_e32 v15, 0xd0, v76
	v_xor_b32_e32 v16, 0xe0, v76
	v_xor_b32_e32 v17, 0xf0, v76
	v_mov_b32_e32 v78, 0x3db504f3
	v_mov_b32_e32 v79, 0x3db504f3
	ds_read_u16 v54, v2
	ds_read_u16 v62, v2 offset:16384
	ds_read_u16 v55, v3 offset:256
	ds_read_u16 v63, v3 offset:16640
	ds_read_u16 v56, v4 offset:512
	ds_read_u16 v64, v4 offset:16896
	ds_read_u16 v57, v5 offset:768
	ds_read_u16 v65, v5 offset:17152
	ds_read_u16 v58, v6 offset:1024
	ds_read_u16 v66, v6 offset:17408
	ds_read_u16 v59, v7 offset:1280
	ds_read_u16 v67, v7 offset:17664
	ds_read_u16 v60, v8 offset:1536
	ds_read_u16 v68, v8 offset:17920
	ds_read_u16 v61, v9 offset:1792
	ds_read_u16 v69, v9 offset:18176
	s_waitcnt lgkmcnt(0)
	v_mov_b32_e32 v81, v80
	ds_read_u16 v94, v10 offset:2048
	ds_read_u16 v102, v10 offset:18432
	ds_read_u16 v95, v11 offset:2304
	ds_read_u16 v103, v11 offset:18688
	ds_read_u16 v96, v12 offset:2560
	ds_read_u16 v104, v12 offset:18944
	ds_read_u16 v97, v13 offset:2816
	ds_read_u16 v105, v13 offset:19200
	ds_read_u16 v98, v14 offset:3072
	ds_read_u16 v106, v14 offset:19456
	ds_read_u16 v99, v15 offset:3328
	ds_read_u16 v107, v15 offset:19712
	ds_read_u16 v100, v16 offset:3584
	ds_read_u16 v108, v16 offset:19968
	ds_read_u16 v101, v17 offset:3840
	ds_read_u16 v109, v17 offset:20224
	v_lshlrev_b32_e32 v70, 16, v18
	v_and_b32_e32 v71, 0xffff0000, v18
	v_rcp_f32_e32 v72, v70
	v_rcp_f32_e32 v73, v71
	v_lshlrev_b32_e32 v54, 16, v54
	v_lshlrev_b32_e32 v55, 16, v55
	v_lshlrev_b32_e32 v62, 16, v62
	v_lshlrev_b32_e32 v63, 16, v63
	v_pk_mul_f32 v[54:55], v[54:55], v[78:79] op_sel_hi:[1,0]
	v_pk_mul_f32 v[62:63], v[72:73], v[62:63]
	v_pk_mul_f32 v[54:55], v[54:55], v[70:71]
	v_pk_mul_f32 v[70:71], v[80:81], v[62:63] op_sel_hi:[0,1]
	v_cvt_pk_bf16_f32 v54, v54, v55
	v_cvt_pk_bf16_f32 v62, v62, v63
	v_cvt_pk_bf16_f32 v110, v70, v71
	ds_write_b16 v2, v54
	ds_write_b16_d16_hi v3, v54 offset:256
	ds_write_b16 v2, v62 offset:16384
	ds_write_b16_d16_hi v3, v62 offset:16640
	v_lshlrev_b32_e32 v70, 16, v19
	v_and_b32_e32 v71, 0xffff0000, v19
	v_rcp_f32_e32 v72, v70
	v_rcp_f32_e32 v73, v71
	v_lshlrev_b32_e32 v56, 16, v56
	v_lshlrev_b32_e32 v57, 16, v57
	v_lshlrev_b32_e32 v64, 16, v64
	v_lshlrev_b32_e32 v65, 16, v65
	v_pk_mul_f32 v[56:57], v[56:57], v[78:79] op_sel_hi:[1,0]
	v_pk_mul_f32 v[64:65], v[72:73], v[64:65]
	v_pk_mul_f32 v[56:57], v[56:57], v[70:71]
	v_pk_mul_f32 v[70:71], v[80:81], v[64:65] op_sel_hi:[0,1]
	v_cvt_pk_bf16_f32 v56, v56, v57
	v_cvt_pk_bf16_f32 v64, v64, v65
	v_cvt_pk_bf16_f32 v111, v70, v71
	ds_write_b16 v4, v56 offset:512
	ds_write_b16_d16_hi v5, v56 offset:768
	ds_write_b16 v4, v64 offset:16896
	ds_write_b16_d16_hi v5, v64 offset:17152
	v_lshlrev_b32_e32 v70, 16, v20
	v_and_b32_e32 v71, 0xffff0000, v20
	v_rcp_f32_e32 v72, v70
	v_rcp_f32_e32 v73, v71
	v_lshlrev_b32_e32 v58, 16, v58
	v_lshlrev_b32_e32 v59, 16, v59
	v_lshlrev_b32_e32 v66, 16, v66
	v_lshlrev_b32_e32 v67, 16, v67
	v_pk_mul_f32 v[58:59], v[58:59], v[78:79] op_sel_hi:[1,0]
	v_pk_mul_f32 v[66:67], v[72:73], v[66:67]
	v_pk_mul_f32 v[58:59], v[58:59], v[70:71]
	v_pk_mul_f32 v[70:71], v[80:81], v[66:67] op_sel_hi:[0,1]
	v_cvt_pk_bf16_f32 v58, v58, v59
	v_cvt_pk_bf16_f32 v66, v66, v67
	v_cvt_pk_bf16_f32 v112, v70, v71
	ds_write_b16 v6, v58 offset:1024
	ds_write_b16_d16_hi v7, v58 offset:1280
	ds_write_b16 v6, v66 offset:17408
	ds_write_b16_d16_hi v7, v66 offset:17664
	v_lshlrev_b32_e32 v70, 16, v21
	v_and_b32_e32 v71, 0xffff0000, v21
	v_rcp_f32_e32 v72, v70
	v_rcp_f32_e32 v73, v71
	v_lshlrev_b32_e32 v60, 16, v60
	v_lshlrev_b32_e32 v61, 16, v61
	v_lshlrev_b32_e32 v68, 16, v68
	v_lshlrev_b32_e32 v69, 16, v69
	v_pk_mul_f32 v[60:61], v[60:61], v[78:79] op_sel_hi:[1,0]
	v_pk_mul_f32 v[68:69], v[72:73], v[68:69]
	v_pk_mul_f32 v[60:61], v[60:61], v[70:71]
	v_pk_mul_f32 v[70:71], v[80:81], v[68:69] op_sel_hi:[0,1]
	v_cvt_pk_bf16_f32 v60, v60, v61
	v_cvt_pk_bf16_f32 v68, v68, v69
	v_cvt_pk_bf16_f32 v113, v70, v71
	ds_write_b16 v8, v60 offset:1536
	ds_write_b16_d16_hi v9, v60 offset:1792
	ds_write_b16 v8, v68 offset:17920
	ds_write_b16_d16_hi v9, v68 offset:18176
	ds_write_b128 v34, v[110:113] offset:32768
	s_waitcnt lgkmcnt(15)
	ds_read_u16 v54, v2 offset:4096
	ds_read_u16 v62, v2 offset:20480
	ds_read_u16 v55, v3 offset:4352
	ds_read_u16 v63, v3 offset:20736
	ds_read_u16 v56, v4 offset:4608
	ds_read_u16 v64, v4 offset:20992
	ds_read_u16 v57, v5 offset:4864
	ds_read_u16 v65, v5 offset:21248
	ds_read_u16 v58, v6 offset:5120
	ds_read_u16 v66, v6 offset:21504
	ds_read_u16 v59, v7 offset:5376
	ds_read_u16 v67, v7 offset:21760
	ds_read_u16 v60, v8 offset:5632
	ds_read_u16 v68, v8 offset:22016
	ds_read_u16 v61, v9 offset:5888
	ds_read_u16 v69, v9 offset:22272
	v_lshlrev_b32_e32 v70, 16, v22
	v_and_b32_e32 v71, 0xffff0000, v22
	v_rcp_f32_e32 v72, v70
	v_rcp_f32_e32 v73, v71
	v_lshlrev_b32_e32 v94, 16, v94
	v_lshlrev_b32_e32 v95, 16, v95
	v_lshlrev_b32_e32 v102, 16, v102
	v_lshlrev_b32_e32 v103, 16, v103
	v_pk_mul_f32 v[94:95], v[94:95], v[78:79] op_sel_hi:[1,0]
	v_pk_mul_f32 v[102:103], v[72:73], v[102:103]
	v_pk_mul_f32 v[94:95], v[94:95], v[70:71]
	v_pk_mul_f32 v[70:71], v[80:81], v[102:103] op_sel_hi:[0,1]
	v_cvt_pk_bf16_f32 v94, v94, v95
	v_cvt_pk_bf16_f32 v102, v102, v103
	v_cvt_pk_bf16_f32 v110, v70, v71
	ds_write_b16 v10, v94 offset:2048
	ds_write_b16_d16_hi v11, v94 offset:2304
	ds_write_b16 v10, v102 offset:18432
	ds_write_b16_d16_hi v11, v102 offset:18688
	v_lshlrev_b32_e32 v70, 16, v23
	v_and_b32_e32 v71, 0xffff0000, v23
	v_rcp_f32_e32 v72, v70
	v_rcp_f32_e32 v73, v71
	v_lshlrev_b32_e32 v96, 16, v96
	v_lshlrev_b32_e32 v97, 16, v97
	v_lshlrev_b32_e32 v104, 16, v104
	v_lshlrev_b32_e32 v105, 16, v105
	v_pk_mul_f32 v[96:97], v[96:97], v[78:79] op_sel_hi:[1,0]
	v_pk_mul_f32 v[104:105], v[72:73], v[104:105]
	v_pk_mul_f32 v[96:97], v[96:97], v[70:71]
	v_pk_mul_f32 v[70:71], v[80:81], v[104:105] op_sel_hi:[0,1]
	v_cvt_pk_bf16_f32 v96, v96, v97
	v_cvt_pk_bf16_f32 v104, v104, v105
	v_cvt_pk_bf16_f32 v111, v70, v71
	ds_write_b16 v12, v96 offset:2560
	ds_write_b16_d16_hi v13, v96 offset:2816
	ds_write_b16 v12, v104 offset:18944
	ds_write_b16_d16_hi v13, v104 offset:19200
	v_lshlrev_b32_e32 v70, 16, v24
	v_and_b32_e32 v71, 0xffff0000, v24
	v_rcp_f32_e32 v72, v70
	v_rcp_f32_e32 v73, v71
	v_lshlrev_b32_e32 v98, 16, v98
	v_lshlrev_b32_e32 v99, 16, v99
	v_lshlrev_b32_e32 v106, 16, v106
	v_lshlrev_b32_e32 v107, 16, v107
	v_pk_mul_f32 v[98:99], v[98:99], v[78:79] op_sel_hi:[1,0]
	v_pk_mul_f32 v[106:107], v[72:73], v[106:107]
	v_pk_mul_f32 v[98:99], v[98:99], v[70:71]
	v_pk_mul_f32 v[70:71], v[80:81], v[106:107] op_sel_hi:[0,1]
	v_cvt_pk_bf16_f32 v98, v98, v99
	v_cvt_pk_bf16_f32 v106, v106, v107
	v_cvt_pk_bf16_f32 v112, v70, v71
	ds_write_b16 v14, v98 offset:3072
	ds_write_b16_d16_hi v15, v98 offset:3328
	ds_write_b16 v14, v106 offset:19456
	ds_write_b16_d16_hi v15, v106 offset:19712
	v_lshlrev_b32_e32 v70, 16, v25
	v_and_b32_e32 v71, 0xffff0000, v25
	v_rcp_f32_e32 v72, v70
	v_rcp_f32_e32 v73, v71
	v_lshlrev_b32_e32 v100, 16, v100
	v_lshlrev_b32_e32 v101, 16, v101
	v_lshlrev_b32_e32 v108, 16, v108
	v_lshlrev_b32_e32 v109, 16, v109
	v_pk_mul_f32 v[100:101], v[100:101], v[78:79] op_sel_hi:[1,0]
	v_pk_mul_f32 v[108:109], v[72:73], v[108:109]
	v_pk_mul_f32 v[100:101], v[100:101], v[70:71]
	v_pk_mul_f32 v[70:71], v[80:81], v[108:109] op_sel_hi:[0,1]
	v_cvt_pk_bf16_f32 v100, v100, v101
	v_cvt_pk_bf16_f32 v108, v108, v109
	v_cvt_pk_bf16_f32 v113, v70, v71
	ds_write_b16 v16, v100 offset:3584
	ds_write_b16_d16_hi v17, v100 offset:3840
	ds_write_b16 v16, v108 offset:19968
	ds_write_b16_d16_hi v17, v108 offset:20224
	ds_write_b128 v35, v[110:113] offset:32768
	s_waitcnt lgkmcnt(15)
	ds_read_u16 v94, v10 offset:6144
	ds_read_u16 v102, v10 offset:22528
	ds_read_u16 v95, v11 offset:6400
	ds_read_u16 v103, v11 offset:22784
	ds_read_u16 v96, v12 offset:6656
	ds_read_u16 v104, v12 offset:23040
	ds_read_u16 v97, v13 offset:6912
	ds_read_u16 v105, v13 offset:23296
	ds_read_u16 v98, v14 offset:7168
	ds_read_u16 v106, v14 offset:23552
	ds_read_u16 v99, v15 offset:7424
	ds_read_u16 v107, v15 offset:23808
	ds_read_u16 v100, v16 offset:7680
	ds_read_u16 v108, v16 offset:24064
	ds_read_u16 v101, v17 offset:7936
	ds_read_u16 v109, v17 offset:24320
	v_lshlrev_b32_e32 v70, 16, v26
	v_and_b32_e32 v71, 0xffff0000, v26
	v_rcp_f32_e32 v72, v70
	v_rcp_f32_e32 v73, v71
	v_lshlrev_b32_e32 v54, 16, v54
	v_lshlrev_b32_e32 v55, 16, v55
	v_lshlrev_b32_e32 v62, 16, v62
	v_lshlrev_b32_e32 v63, 16, v63
	v_pk_mul_f32 v[54:55], v[54:55], v[78:79] op_sel_hi:[1,0]
	v_pk_mul_f32 v[62:63], v[72:73], v[62:63]
	v_pk_mul_f32 v[54:55], v[54:55], v[70:71]
	v_pk_mul_f32 v[70:71], v[80:81], v[62:63] op_sel_hi:[0,1]
	v_cvt_pk_bf16_f32 v54, v54, v55
	v_cvt_pk_bf16_f32 v62, v62, v63
	v_cvt_pk_bf16_f32 v110, v70, v71
	ds_write_b16 v2, v54 offset:4096
	ds_write_b16_d16_hi v3, v54 offset:4352
	ds_write_b16 v2, v62 offset:20480
	ds_write_b16_d16_hi v3, v62 offset:20736
	v_lshlrev_b32_e32 v70, 16, v27
	v_and_b32_e32 v71, 0xffff0000, v27
	v_rcp_f32_e32 v72, v70
	v_rcp_f32_e32 v73, v71
	v_lshlrev_b32_e32 v56, 16, v56
	v_lshlrev_b32_e32 v57, 16, v57
	v_lshlrev_b32_e32 v64, 16, v64
	v_lshlrev_b32_e32 v65, 16, v65
	v_pk_mul_f32 v[56:57], v[56:57], v[78:79] op_sel_hi:[1,0]
	v_pk_mul_f32 v[64:65], v[72:73], v[64:65]
	v_pk_mul_f32 v[56:57], v[56:57], v[70:71]
	v_pk_mul_f32 v[70:71], v[80:81], v[64:65] op_sel_hi:[0,1]
	v_cvt_pk_bf16_f32 v56, v56, v57
	v_cvt_pk_bf16_f32 v64, v64, v65
	v_cvt_pk_bf16_f32 v111, v70, v71
	ds_write_b16 v4, v56 offset:4608
	ds_write_b16_d16_hi v5, v56 offset:4864
	ds_write_b16 v4, v64 offset:20992
	ds_write_b16_d16_hi v5, v64 offset:21248
	v_lshlrev_b32_e32 v70, 16, v28
	v_and_b32_e32 v71, 0xffff0000, v28
	v_rcp_f32_e32 v72, v70
	v_rcp_f32_e32 v73, v71
	v_lshlrev_b32_e32 v58, 16, v58
	v_lshlrev_b32_e32 v59, 16, v59
	v_lshlrev_b32_e32 v66, 16, v66
	v_lshlrev_b32_e32 v67, 16, v67
	v_pk_mul_f32 v[58:59], v[58:59], v[78:79] op_sel_hi:[1,0]
	v_pk_mul_f32 v[66:67], v[72:73], v[66:67]
	v_pk_mul_f32 v[58:59], v[58:59], v[70:71]
	v_pk_mul_f32 v[70:71], v[80:81], v[66:67] op_sel_hi:[0,1]
	v_cvt_pk_bf16_f32 v58, v58, v59
	v_cvt_pk_bf16_f32 v66, v66, v67
	v_cvt_pk_bf16_f32 v112, v70, v71
	ds_write_b16 v6, v58 offset:5120
	ds_write_b16_d16_hi v7, v58 offset:5376
	ds_write_b16 v6, v66 offset:21504
	ds_write_b16_d16_hi v7, v66 offset:21760
	v_lshlrev_b32_e32 v70, 16, v29
	v_and_b32_e32 v71, 0xffff0000, v29
	v_rcp_f32_e32 v72, v70
	v_rcp_f32_e32 v73, v71
	v_lshlrev_b32_e32 v60, 16, v60
	v_lshlrev_b32_e32 v61, 16, v61
	v_lshlrev_b32_e32 v68, 16, v68
	v_lshlrev_b32_e32 v69, 16, v69
	v_pk_mul_f32 v[60:61], v[60:61], v[78:79] op_sel_hi:[1,0]
	v_pk_mul_f32 v[68:69], v[72:73], v[68:69]
	v_pk_mul_f32 v[60:61], v[60:61], v[70:71]
	v_pk_mul_f32 v[70:71], v[80:81], v[68:69] op_sel_hi:[0,1]
	v_cvt_pk_bf16_f32 v60, v60, v61
	v_cvt_pk_bf16_f32 v68, v68, v69
	v_cvt_pk_bf16_f32 v113, v70, v71
	ds_write_b16 v8, v60 offset:5632
	ds_write_b16_d16_hi v9, v60 offset:5888
	ds_write_b16 v8, v68 offset:22016
	ds_write_b16_d16_hi v9, v68 offset:22272
	ds_write_b128 v36, v[110:113] offset:32768
	s_waitcnt lgkmcnt(15)
	v_lshlrev_b32_e32 v70, 16, v30
	v_and_b32_e32 v71, 0xffff0000, v30
	v_rcp_f32_e32 v72, v70
	v_rcp_f32_e32 v73, v71
	v_lshlrev_b32_e32 v94, 16, v94
	v_lshlrev_b32_e32 v95, 16, v95
	v_lshlrev_b32_e32 v102, 16, v102
	v_lshlrev_b32_e32 v103, 16, v103
	v_pk_mul_f32 v[94:95], v[94:95], v[78:79] op_sel_hi:[1,0]
	v_pk_mul_f32 v[102:103], v[72:73], v[102:103]
	v_pk_mul_f32 v[94:95], v[94:95], v[70:71]
	v_pk_mul_f32 v[70:71], v[80:81], v[102:103] op_sel_hi:[0,1]
	v_cvt_pk_bf16_f32 v94, v94, v95
	v_cvt_pk_bf16_f32 v102, v102, v103
	v_cvt_pk_bf16_f32 v110, v70, v71
	ds_write_b16 v10, v94 offset:6144
	ds_write_b16_d16_hi v11, v94 offset:6400
	ds_write_b16 v10, v102 offset:22528
	ds_write_b16_d16_hi v11, v102 offset:22784
	v_lshlrev_b32_e32 v70, 16, v31
	v_and_b32_e32 v71, 0xffff0000, v31
	v_rcp_f32_e32 v72, v70
	v_rcp_f32_e32 v73, v71
	v_lshlrev_b32_e32 v96, 16, v96
	v_lshlrev_b32_e32 v97, 16, v97
	v_lshlrev_b32_e32 v104, 16, v104
	v_lshlrev_b32_e32 v105, 16, v105
	v_pk_mul_f32 v[96:97], v[96:97], v[78:79] op_sel_hi:[1,0]
	v_pk_mul_f32 v[104:105], v[72:73], v[104:105]
	v_pk_mul_f32 v[96:97], v[96:97], v[70:71]
	v_pk_mul_f32 v[70:71], v[80:81], v[104:105] op_sel_hi:[0,1]
	v_cvt_pk_bf16_f32 v96, v96, v97
	v_cvt_pk_bf16_f32 v104, v104, v105
	v_cvt_pk_bf16_f32 v111, v70, v71
	ds_write_b16 v12, v96 offset:6656
	ds_write_b16_d16_hi v13, v96 offset:6912
	ds_write_b16 v12, v104 offset:23040
	ds_write_b16_d16_hi v13, v104 offset:23296
	v_lshlrev_b32_e32 v70, 16, v32
	v_and_b32_e32 v71, 0xffff0000, v32
	v_rcp_f32_e32 v72, v70
	v_rcp_f32_e32 v73, v71
	v_lshlrev_b32_e32 v98, 16, v98
	v_lshlrev_b32_e32 v99, 16, v99
	v_lshlrev_b32_e32 v106, 16, v106
	v_lshlrev_b32_e32 v107, 16, v107
	v_pk_mul_f32 v[98:99], v[98:99], v[78:79] op_sel_hi:[1,0]
	v_pk_mul_f32 v[106:107], v[72:73], v[106:107]
	v_pk_mul_f32 v[98:99], v[98:99], v[70:71]
	v_pk_mul_f32 v[70:71], v[80:81], v[106:107] op_sel_hi:[0,1]
	v_cvt_pk_bf16_f32 v98, v98, v99
	v_cvt_pk_bf16_f32 v106, v106, v107
	v_cvt_pk_bf16_f32 v112, v70, v71
	ds_write_b16 v14, v98 offset:7168
	ds_write_b16_d16_hi v15, v98 offset:7424
	ds_write_b16 v14, v106 offset:23552
	ds_write_b16_d16_hi v15, v106 offset:23808
	v_lshlrev_b32_e32 v70, 16, v33
	v_and_b32_e32 v71, 0xffff0000, v33
	v_rcp_f32_e32 v72, v70
	v_rcp_f32_e32 v73, v71
	v_lshlrev_b32_e32 v100, 16, v100
	v_lshlrev_b32_e32 v101, 16, v101
	v_lshlrev_b32_e32 v108, 16, v108
	v_lshlrev_b32_e32 v109, 16, v109
	v_pk_mul_f32 v[100:101], v[100:101], v[78:79] op_sel_hi:[1,0]
	v_pk_mul_f32 v[108:109], v[72:73], v[108:109]
	v_pk_mul_f32 v[100:101], v[100:101], v[70:71]
	v_pk_mul_f32 v[70:71], v[80:81], v[108:109] op_sel_hi:[0,1]
	v_cvt_pk_bf16_f32 v100, v100, v101
	v_cvt_pk_bf16_f32 v108, v108, v109
	v_cvt_pk_bf16_f32 v113, v70, v71
	ds_write_b16 v16, v100 offset:7680
	ds_write_b16_d16_hi v17, v100 offset:7936
	ds_write_b16 v16, v108 offset:24064
	ds_write_b16_d16_hi v17, v108 offset:24320
	ds_write_b128 v37, v[110:113] offset:32768
	v_lshlrev_b32_e32 v87, 1, v89
	v_and_b32_e32 v87, 14, v87
	v_and_b32_e32 v92, 15, v89
	s_movk_i32 s0, 0xb0
	s_add_i32 s31, s15, 1
	s_cmp_eq_u32 s28, -1
	s_waitcnt lgkmcnt(0)
	s_barrier
	s_cbranch_scc1 .LBB0_474
	s_cmp_gt_u32 s15, 2
	s_mov_b64 s[16:17], -1
	s_cbranch_scc0 .LBB0_469
	s_add_i32 s15, s15, -3
	s_and_b64 s[0:1], s[4:5], exec
	s_cselect_b32 s0, s15, s28
	s_mov_b64 s[16:17], 0

.LBB0_508:
	s_and_b64 vcc, exec, s[4:5]
	s_cbranch_vccz .LBB0_634
	s_mov_b32 s98, 0x3e38aa3b
	s_mov_b32 s99, 0x3e38aa3b
	v_readlane_b32 s100, v255, 12
	s_nop 3
	s_cmpk_lt_u32 s100, 0x100
	s_cbranch_scc1 .Lprio_skip_ev
	s_setprio 1

.LBB0_590:
	v_mov_b64_e32 v[154:155], v[2:3]
	v_pk_fma_f32 v[136:137], v[136:137], s[98:99], v[152:153] op_sel_hi:[1,1,0] neg_lo:[0,0,1] neg_hi:[0,0,1]
	v_pk_fma_f32 v[138:139], v[138:139], s[98:99], v[152:153] op_sel_hi:[1,1,0] neg_lo:[0,0,1] neg_hi:[0,0,1]
	v_pk_fma_f32 v[132:133], v[132:133], s[98:99], v[152:153] op_sel_hi:[1,1,0] neg_lo:[0,0,1] neg_hi:[0,0,1]
	v_pk_fma_f32 v[134:135], v[134:135], s[98:99], v[152:153] op_sel_hi:[1,1,0] neg_lo:[0,0,1] neg_hi:[0,0,1]
	v_exp_f32_e32 v136, v136
	v_exp_f32_e32 v137, v137
	v_exp_f32_e32 v138, v138
	v_exp_f32_e32 v139, v139
	v_exp_f32_e32 v168, v132
	v_exp_f32_e32 v169, v133
	v_exp_f32_e32 v170, v134
	v_exp_f32_e32 v171, v135
	v_pk_add_f32 v[166:167], v[136:137], 0 op_sel_hi:[1,0]
	v_cvt_pk_bf16_f32 v134, v168, v169
	v_pk_add_f32 v[166:167], v[138:139], v[166:167]
	v_fma_f32 v124, v124, s72, -v3
	v_fma_f32 v125, v125, s72, -v3
	v_pk_add_f32 v[132:133], v[168:169], v[166:167]
	v_fma_f32 v126, v126, s72, -v3
	v_fma_f32 v127, v127, s72, -v3
	v_pk_add_f32 v[132:133], v[170:171], v[132:133]
	v_fma_f32 v128, v128, s72, -v3
	v_fma_f32 v129, v129, s72, -v3
	v_add_f32_e32 v2, v132, v133
	v_add_f32_e32 v0, v0, v2
	v_add_u32_e32 v2, s28, v160
	v_add_u32_e32 v152, v2, v159
	ds_read_b128 v[166:169], v152 offset:8192
	v_fma_f32 v130, v130, s72, -v3
	v_fma_f32 v131, v131, s72, -v3
	v_exp_f32_e32 v124, v124
	v_exp_f32_e32 v125, v125
	v_exp_f32_e32 v126, v126
	v_exp_f32_e32 v127, v127
	v_exp_f32_e32 v128, v128
	v_exp_f32_e32 v129, v129
	v_exp_f32_e32 v130, v130
	v_exp_f32_e32 v131, v131
	v_cvt_pk_bf16_f32 v132, v136, v137
	v_cvt_pk_bf16_f32 v133, v138, v139
	v_cvt_pk_bf16_f32 v135, v170, v171
	ds_read_b128 v[170:173], v152 offset:10240
	v_cvt_pk_bf16_f32 v136, v124, v125
	v_cvt_pk_bf16_f32 v137, v126, v127
	v_cvt_pk_bf16_f32 v138, v128, v129
	v_cvt_pk_bf16_f32 v139, v130, v131
	v_pk_add_f32 v[124:125], v[124:125], 0 op_sel_hi:[1,0]
	s_nop 0
	v_pk_add_f32 v[124:125], v[126:127], v[124:125]
	s_nop 0
	v_pk_add_f32 v[124:125], v[128:129], v[124:125]
	s_nop 0
	v_pk_add_f32 v[124:125], v[130:131], v[124:125]
	s_nop 0
	v_add_f32_e32 v124, v124, v125
	ds_read_b128 v[126:129], v152 offset:12288
	s_waitcnt lgkmcnt(2)
	v_mfma_f32_16x16x32_bf16 v[80:83], v[166:169], v[132:135], v[80:83]
	v_mfma_f32_16x16x32_bf16 v[76:79], v[166:169], v[136:139], v[76:79]
	ds_read_b128 v[166:169], v152 offset:14336
	s_waitcnt lgkmcnt(2)
	v_mfma_f32_16x16x32_bf16 v[72:75], v[170:173], v[132:135], v[72:75]
	v_mfma_f32_16x16x32_bf16 v[68:71], v[170:173], v[136:139], v[68:71]
	ds_read_b128 v[170:173], v152 offset:16384
	s_waitcnt lgkmcnt(2)
	v_mfma_f32_16x16x32_bf16 v[64:67], v[126:129], v[132:135], v[64:67]
	v_mfma_f32_16x16x32_bf16 v[60:63], v[126:129], v[136:139], v[60:63]
	ds_read_b128 v[126:129], v152 offset:18432
	s_waitcnt lgkmcnt(2)
	v_mfma_f32_16x16x32_bf16 v[56:59], v[166:169], v[132:135], v[56:59]
	v_mfma_f32_16x16x32_bf16 v[52:55], v[166:169], v[136:139], v[52:55]
	ds_read_b128 v[166:169], v152 offset:20480
	s_waitcnt lgkmcnt(2)
	v_mfma_f32_16x16x32_bf16 v[48:51], v[170:173], v[132:135], v[48:51]
	v_mfma_f32_16x16x32_bf16 v[44:47], v[170:173], v[136:139], v[44:47]
	ds_read_b128 v[170:173], v152 offset:22528
	s_waitcnt lgkmcnt(2)
	v_mfma_f32_16x16x32_bf16 v[40:43], v[126:129], v[132:135], v[40:43]
	v_mfma_f32_16x16x32_bf16 v[32:35], v[126:129], v[136:139], v[32:35]
	s_waitcnt lgkmcnt(1)
	v_mfma_f32_16x16x32_bf16 v[36:39], v[166:169], v[132:135], v[36:39]
	v_mfma_f32_16x16x32_bf16 v[24:27], v[166:169], v[136:139], v[24:27]
	s_waitcnt lgkmcnt(0)
	v_mfma_f32_16x16x32_bf16 v[28:31], v[170:173], v[132:135], v[28:31]
	v_max3_f32 v132, v116, v117, v118
	v_add_f32_e32 v133, 0x41000000, v165
	v_max3_f32 v132, v132, v119, v120
	v_mfma_f32_16x16x32_bf16 v[20:23], v[170:173], v[136:139], v[20:23]
	v_max3_f32 v132, v132, v121, v122
	s_nop 0
	v_max3_f32 v132, v132, v123, v123
	s_nop 0
	v_mul_f32_e32 v132, 0x3e38aa3b, v132
	v_cmp_gt_f32_e32 vcc, v132, v133
	s_cbranch_vccz .LBB0_592
	ds_swizzle_b32 v3, v132 offset:swizzle(SWAP,16)
	v_max_f32_e32 v132, v132, v132
	s_waitcnt lgkmcnt(0)
	v_max_f32_e32 v3, v3, v3
	v_max_f32_e32 v3, v132, v3
	ds_bpermute_b32 v132, v156, v3
	s_waitcnt lgkmcnt(0)
	v_max3_f32 v154, v165, v3, v132
	v_sub_f32_e32 v3, v165, v154
	v_exp_f32_e32 v132, v3
	v_mov_b32_e32 v3, v155
	v_mov_b32_e32 v165, v154
	v_mul_f32_e32 v0, v0, v132
	v_pk_mul_f32 v[82:83], v[82:83], v[132:133] op_sel_hi:[1,0]
	v_pk_mul_f32 v[80:81], v[80:81], v[132:133] op_sel_hi:[1,0]
	v_pk_mul_f32 v[74:75], v[74:75], v[132:133] op_sel_hi:[1,0]
	v_pk_mul_f32 v[72:73], v[72:73], v[132:133] op_sel_hi:[1,0]
	v_pk_mul_f32 v[66:67], v[66:67], v[132:133] op_sel_hi:[1,0]
	v_pk_mul_f32 v[64:65], v[64:65], v[132:133] op_sel_hi:[1,0]
	v_pk_mul_f32 v[58:59], v[58:59], v[132:133] op_sel_hi:[1,0]
	v_pk_mul_f32 v[56:57], v[56:57], v[132:133] op_sel_hi:[1,0]
	v_pk_mul_f32 v[50:51], v[50:51], v[132:133] op_sel_hi:[1,0]
	v_pk_mul_f32 v[48:49], v[48:49], v[132:133] op_sel_hi:[1,0]
	v_pk_mul_f32 v[42:43], v[42:43], v[132:133] op_sel_hi:[1,0]
	v_pk_mul_f32 v[40:41], v[40:41], v[132:133] op_sel_hi:[1,0]
	v_pk_mul_f32 v[38:39], v[38:39], v[132:133] op_sel_hi:[1,0]
	v_pk_mul_f32 v[36:37], v[36:37], v[132:133] op_sel_hi:[1,0]
	v_pk_mul_f32 v[30:31], v[30:31], v[132:133] op_sel_hi:[1,0]
	v_pk_mul_f32 v[28:29], v[28:29], v[132:133] op_sel_hi:[1,0]

.LBB0_594:
	v_fma_f32 v116, v116, s72, -v165
	v_fma_f32 v117, v117, s72, -v165
	v_fma_f32 v118, v118, s72, -v165
	v_fma_f32 v119, v119, s72, -v165
	v_fma_f32 v120, v120, s72, -v165
	v_fma_f32 v121, v121, s72, -v165
	v_fma_f32 v108, v108, s72, -v3
	v_fma_f32 v109, v109, s72, -v3
	v_exp_f32_e32 v116, v116
	v_exp_f32_e32 v117, v117
	v_exp_f32_e32 v118, v118
	v_exp_f32_e32 v119, v119
	v_fma_f32 v110, v110, s72, -v3
	v_fma_f32 v111, v111, s72, -v3
	v_exp_f32_e32 v120, v120
	v_exp_f32_e32 v121, v121
	v_exp_f32_e32 v108, v108
	v_exp_f32_e32 v109, v109
	v_fma_f32 v112, v112, s72, -v3
	v_fma_f32 v113, v113, s72, -v3
	v_exp_f32_e32 v110, v110
	v_exp_f32_e32 v111, v111
	v_pk_add_f32 v[126:127], v[116:117], 0 op_sel_hi:[1,0]
	v_exp_f32_e32 v112, v112
	v_exp_f32_e32 v113, v113
	v_fma_f32 v114, v114, s72, -v3
	v_fma_f32 v115, v115, s72, -v3
	v_pk_add_f32 v[126:127], v[118:119], v[126:127]
	v_exp_f32_e32 v114, v114
	v_exp_f32_e32 v115, v115
	v_pk_add_f32 v[126:127], v[120:121], v[126:127]
	v_cvt_pk_bf16_f32 v116, v116, v117
	v_cvt_pk_bf16_f32 v117, v118, v119
	v_cvt_pk_bf16_f32 v118, v120, v121
	v_pk_add_f32 v[120:121], v[108:109], 0 op_sel_hi:[1,0]
	v_add_u32_e32 v2, v2, v157
	v_pk_add_f32 v[120:121], v[110:111], v[120:121]
	v_cvt_pk_bf16_f32 v108, v108, v109
	v_pk_add_f32 v[120:121], v[112:113], v[120:121]
	v_cvt_pk_bf16_f32 v109, v110, v111
	v_pk_add_f32 v[120:121], v[114:115], v[120:121]
	v_cvt_pk_bf16_f32 v110, v112, v113
	v_cvt_pk_bf16_f32 v111, v114, v115
	ds_read_b128 v[112:115], v2 offset:8192
	ds_read_b128 v[128:131], v2 offset:10240
	ds_read_b128 v[132:135], v2 offset:12288
	ds_read_b128 v[136:139], v2 offset:14336
	v_fma_f32 v122, v122, s72, -v165
	v_fma_f32 v123, v123, s72, -v165
	s_nop 0
	v_exp_f32_e32 v122, v122
	v_exp_f32_e32 v123, v123
	s_waitcnt lgkmcnt(3)
	v_mfma_f32_16x16x32_bf16 v[76:79], v[112:115], v[108:111], v[76:79]
	v_cvt_pk_bf16_f32 v119, v122, v123
	s_bitcmp1_b32 s21, 0
	s_cselect_b32 s0, 0x6000, 0
	v_mfma_f32_16x16x32_bf16 v[80:83], v[112:115], v[116:119], v[80:83]
	ds_read_b128 v[112:115], v2 offset:16384
	v_pk_add_f32 v[126:127], v[122:123], v[126:127]
	s_add_i32 s0, s0, 0
	s_waitcnt lgkmcnt(3)
	v_mfma_f32_16x16x32_bf16 v[72:75], v[128:131], v[116:119], v[72:75]
	v_add_f32_e32 v125, v126, v127
	v_add_f32_e32 v120, v120, v121
	v_mov_b64_e32 v[152:153], v[154:155]
	v_mfma_f32_16x16x32_bf16 v[68:71], v[128:131], v[108:111], v[68:71]
	ds_read_b128 v[128:131], v2 offset:18432
	v_add_f32_e32 v0, v0, v125
	v_add_f32_e32 v158, v124, v120
	s_waitcnt lgkmcnt(3)
	v_mfma_f32_16x16x32_bf16 v[64:67], v[132:135], v[116:119], v[64:67]
	s_cmpk_eq_i32 s19, 0x10c0
	v_mfma_f32_16x16x32_bf16 v[60:63], v[132:135], v[108:111], v[60:63]
	ds_read_b128 v[132:135], v2 offset:20480
	s_waitcnt lgkmcnt(3)
	v_mfma_f32_16x16x32_bf16 v[56:59], v[136:139], v[116:119], v[56:59]
	v_mfma_f32_16x16x32_bf16 v[52:55], v[136:139], v[108:111], v[52:55]
	ds_read_b128 v[136:139], v2 offset:22528
	s_waitcnt lgkmcnt(3)
	v_mfma_f32_16x16x32_bf16 v[48:51], v[112:115], v[116:119], v[48:51]
	v_mfma_f32_16x16x32_bf16 v[44:47], v[112:115], v[108:111], v[44:47]
	s_waitcnt lgkmcnt(2)
	v_mfma_f32_16x16x32_bf16 v[40:43], v[128:131], v[116:119], v[40:43]
	v_mfma_f32_16x16x32_bf16 v[32:35], v[128:131], v[108:111], v[32:35]
	v_add_u32_e32 v2, s0, v164
	s_waitcnt vmcnt(5)
	ds_write_b128 v2, v[84:87]
	s_waitcnt vmcnt(4)
	ds_write_b128 v2, v[88:91] offset:4096
	s_waitcnt lgkmcnt(3)
	v_mfma_f32_16x16x32_bf16 v[36:39], v[132:135], v[116:119], v[36:39]
	v_mfma_f32_16x16x32_bf16 v[24:27], v[132:135], v[108:111], v[24:27]
	v_add3_u32 v2, s0, v163, v162
	s_waitcnt vmcnt(3)
	ds_write_b128 v2, v[92:95] offset:8192
	s_waitcnt vmcnt(1)
	ds_write_b128 v2, v[96:99] offset:12288
	s_waitcnt lgkmcnt(4)
	v_mfma_f32_16x16x32_bf16 v[28:31], v[136:139], v[116:119], v[28:31]
	s_waitcnt vmcnt(0)
	ds_write_b128 v2, v[100:103] offset:16384
	ds_write_b128 v2, v[104:107] offset:20480
	v_mfma_f32_16x16x32_bf16 v[20:23], v[136:139], v[108:111], v[20:23]
	s_cbranch_scc1 .LBB0_596
	s_mov_b32 s0, s21
	s_branch .LBB0_580

.LBB0_617:
	v_mov_b64_e32 v[2:3], v[194:195]
	v_pk_fma_f32 v[170:171], v[170:171], s[98:99], v[196:197] op_sel_hi:[1,1,0] neg_lo:[0,0,1] neg_hi:[0,0,1]
	v_pk_fma_f32 v[172:173], v[172:173], s[98:99], v[196:197] op_sel_hi:[1,1,0] neg_lo:[0,0,1] neg_hi:[0,0,1]
	v_pk_fma_f32 v[166:167], v[166:167], s[98:99], v[196:197] op_sel_hi:[1,1,0] neg_lo:[0,0,1] neg_hi:[0,0,1]
	v_pk_fma_f32 v[168:169], v[168:169], s[98:99], v[196:197] op_sel_hi:[1,1,0] neg_lo:[0,0,1] neg_hi:[0,0,1]
	v_exp_f32_e32 v170, v170
	v_exp_f32_e32 v171, v171
	v_exp_f32_e32 v172, v172
	v_exp_f32_e32 v173, v173
	v_exp_f32_e32 v166, v166
	v_exp_f32_e32 v167, v167
	v_exp_f32_e32 v214, v168
	v_exp_f32_e32 v215, v169
	v_pk_add_f32 v[212:213], v[170:171], 0 op_sel_hi:[1,0]
	v_fma_f32 v158, v158, s72, -v195
	v_fma_f32 v159, v159, s72, -v195
	v_pk_add_f32 v[212:213], v[172:173], v[212:213]
	v_fma_f32 v160, v160, s72, -v195
	v_fma_f32 v161, v161, s72, -v195
	v_pk_add_f32 v[168:169], v[166:167], v[212:213]
	v_fma_f32 v162, v162, s72, -v195
	v_fma_f32 v163, v163, s72, -v195
	v_pk_add_f32 v[168:169], v[214:215], v[168:169]
	v_fma_f32 v164, v164, s72, -v195
	v_fma_f32 v165, v165, s72, -v195
	v_add_f32_e32 v168, v168, v169
	v_add_f32_e32 v0, v0, v168
	v_cvt_pk_bf16_f32 v168, v170, v171
	v_cvt_pk_bf16_f32 v170, v166, v167
	v_add_u32_e32 v166, s24, v206
	v_add_u32_e32 v167, v166, v205
	ds_read_b128 v[234:237], v167 offset:8192
	v_exp_f32_e32 v158, v158
	v_exp_f32_e32 v159, v159
	v_exp_f32_e32 v160, v160
	v_exp_f32_e32 v161, v161
	v_exp_f32_e32 v162, v162
	v_exp_f32_e32 v163, v163
	v_exp_f32_e32 v164, v164
	v_exp_f32_e32 v165, v165
	v_cvt_pk_bf16_f32 v169, v172, v173
	v_cvt_pk_bf16_f32 v171, v214, v215
	ds_read_b128 v[212:215], v167 offset:10240
	v_cvt_pk_bf16_f32 v226, v158, v159
	v_cvt_pk_bf16_f32 v227, v160, v161
	v_cvt_pk_bf16_f32 v228, v162, v163
	v_cvt_pk_bf16_f32 v229, v164, v165
	v_pk_add_f32 v[158:159], v[158:159], 0 op_sel_hi:[1,0]
	s_nop 0
	v_pk_add_f32 v[158:159], v[160:161], v[158:159]
	s_nop 0
	v_pk_add_f32 v[158:159], v[162:163], v[158:159]
	s_nop 0
	v_pk_add_f32 v[158:159], v[164:165], v[158:159]
	s_nop 0
	v_add_f32_e32 v158, v158, v159
	ds_read_b128 v[160:163], v167 offset:12288
	s_waitcnt lgkmcnt(2)
	v_mfma_f32_16x16x32_bf16 v[114:117], v[234:237], v[168:171], v[114:117]
	v_mfma_f32_16x16x32_bf16 v[110:113], v[234:237], v[226:229], v[110:113]
	ds_read_b128 v[234:237], v167 offset:14336
	s_waitcnt lgkmcnt(2)
	v_mfma_f32_16x16x32_bf16 v[106:109], v[212:215], v[168:171], v[106:109]
	v_mfma_f32_16x16x32_bf16 v[102:105], v[212:215], v[226:229], v[102:105]
	ds_read_b128 v[212:215], v167 offset:16384
	s_waitcnt lgkmcnt(2)
	v_mfma_f32_16x16x32_bf16 v[98:101], v[160:163], v[168:171], v[98:101]
	v_mfma_f32_16x16x32_bf16 v[94:97], v[160:163], v[226:229], v[94:97]
	ds_read_b128 v[160:163], v167 offset:18432
	s_waitcnt lgkmcnt(2)
	v_mfma_f32_16x16x32_bf16 v[90:93], v[234:237], v[168:171], v[90:93]
	v_mfma_f32_16x16x32_bf16 v[86:89], v[234:237], v[226:229], v[86:89]
	ds_read_b128 v[234:237], v167 offset:20480
	s_waitcnt lgkmcnt(2)
	v_mfma_f32_16x16x32_bf16 v[82:85], v[212:215], v[168:171], v[82:85]
	v_mfma_f32_16x16x32_bf16 v[78:81], v[212:215], v[226:229], v[78:81]
	ds_read_b128 v[212:215], v167 offset:22528
	s_waitcnt lgkmcnt(2)
	v_mfma_f32_16x16x32_bf16 v[74:77], v[160:163], v[168:171], v[74:77]
	v_mfma_f32_16x16x32_bf16 v[66:69], v[160:163], v[226:229], v[66:69]
	s_waitcnt lgkmcnt(1)
	v_mfma_f32_16x16x32_bf16 v[70:73], v[234:237], v[168:171], v[70:73]
	v_mfma_f32_16x16x32_bf16 v[58:61], v[234:237], v[226:229], v[58:61]
	v_max3_f32 v167, v150, v151, v152
	s_nop 0
	v_max3_f32 v167, v167, v153, v154
	s_waitcnt lgkmcnt(0)
	v_mfma_f32_16x16x32_bf16 v[62:65], v[212:215], v[168:171], v[62:65]
	v_max3_f32 v167, v167, v155, v156
	v_add_f32_e32 v168, 0x41000000, v179
	v_max3_f32 v167, v167, v157, v157
	v_mfma_f32_16x16x32_bf16 v[54:57], v[212:215], v[226:229], v[54:57]
	v_mul_f32_e32 v167, 0x3e38aa3b, v167
	v_cmp_gt_f32_e32 vcc, v167, v168
	s_cbranch_vccz .LBB0_619
	ds_swizzle_b32 v2, v167 offset:swizzle(SWAP,16)
	v_max_f32_e32 v167, v167, v167
	v_mov_b32_e32 v195, v3
	s_waitcnt lgkmcnt(0)
	v_max_f32_e32 v2, v2, v2
	v_max_f32_e32 v2, v167, v2
	ds_bpermute_b32 v167, v202, v2
	s_waitcnt lgkmcnt(0)
	v_max3_f32 v2, v179, v2, v167
	v_sub_f32_e32 v167, v179, v2
	v_exp_f32_e32 v168, v167
	v_mov_b32_e32 v179, v2
	v_mul_f32_e32 v0, v0, v168
	v_pk_mul_f32 v[116:117], v[116:117], v[168:169] op_sel_hi:[1,0]
	v_pk_mul_f32 v[114:115], v[114:115], v[168:169] op_sel_hi:[1,0]
	v_pk_mul_f32 v[108:109], v[108:109], v[168:169] op_sel_hi:[1,0]
	v_pk_mul_f32 v[106:107], v[106:107], v[168:169] op_sel_hi:[1,0]
	v_pk_mul_f32 v[100:101], v[100:101], v[168:169] op_sel_hi:[1,0]
	v_pk_mul_f32 v[98:99], v[98:99], v[168:169] op_sel_hi:[1,0]
	v_pk_mul_f32 v[92:93], v[92:93], v[168:169] op_sel_hi:[1,0]
	v_pk_mul_f32 v[90:91], v[90:91], v[168:169] op_sel_hi:[1,0]
	v_pk_mul_f32 v[84:85], v[84:85], v[168:169] op_sel_hi:[1,0]
	v_pk_mul_f32 v[82:83], v[82:83], v[168:169] op_sel_hi:[1,0]
	v_pk_mul_f32 v[76:77], v[76:77], v[168:169] op_sel_hi:[1,0]
	v_pk_mul_f32 v[74:75], v[74:75], v[168:169] op_sel_hi:[1,0]
	v_pk_mul_f32 v[72:73], v[72:73], v[168:169] op_sel_hi:[1,0]
	v_pk_mul_f32 v[70:71], v[70:71], v[168:169] op_sel_hi:[1,0]
	v_pk_mul_f32 v[64:65], v[64:65], v[168:169] op_sel_hi:[1,0]
	v_pk_mul_f32 v[62:63], v[62:63], v[168:169] op_sel_hi:[1,0]

.LBB0_621:
	v_mov_b64_e32 v[196:197], v[2:3]
	v_fma_f32 v150, v150, s72, -v179
	v_fma_f32 v151, v151, s72, -v179
	v_fma_f32 v152, v152, s72, -v179
	v_fma_f32 v153, v153, s72, -v179
	v_fma_f32 v154, v154, s72, -v179
	v_fma_f32 v155, v155, s72, -v179
	v_fma_f32 v156, v156, s72, -v179
	v_fma_f32 v157, v157, s72, -v179
	v_exp_f32_e32 v2, v150
	v_exp_f32_e32 v3, v151
	v_exp_f32_e32 v152, v152
	v_exp_f32_e32 v153, v153
	v_exp_f32_e32 v154, v154
	v_exp_f32_e32 v155, v155
	v_exp_f32_e32 v156, v156
	v_exp_f32_e32 v157, v157
	v_pk_add_f32 v[150:151], v[2:3], 0 op_sel_hi:[1,0]
	v_fma_f32 v146, v146, s72, -v195
	v_fma_f32 v147, v147, s72, -v195
	v_pk_add_f32 v[150:151], v[152:153], v[150:151]
	v_fma_f32 v142, v142, s72, -v195
	v_fma_f32 v143, v143, s72, -v195
	v_pk_add_f32 v[150:151], v[154:155], v[150:151]
	v_exp_f32_e32 v146, v146
	v_pk_add_f32 v[150:151], v[156:157], v[150:151]
	v_exp_f32_e32 v147, v147
	v_add_f32_e32 v150, v150, v151
	v_add_f32_e32 v0, v0, v150
	v_cvt_pk_bf16_f32 v150, v2, v3
	v_fma_f32 v144, v144, s72, -v195
	v_fma_f32 v145, v145, s72, -v195
	v_fma_f32 v148, v148, s72, -v195
	v_fma_f32 v149, v149, s72, -v195
	v_exp_f32_e32 v2, v142
	v_exp_f32_e32 v3, v143
	v_exp_f32_e32 v144, v144
	v_exp_f32_e32 v145, v145
	v_exp_f32_e32 v148, v148
	v_exp_f32_e32 v149, v149
	v_pk_add_f32 v[142:143], v[2:3], 0 op_sel_hi:[1,0]
	v_cvt_pk_bf16_f32 v151, v152, v153
	v_pk_add_f32 v[142:143], v[144:145], v[142:143]
	v_cvt_pk_bf16_f32 v152, v154, v155
	v_pk_add_f32 v[142:143], v[146:147], v[142:143]
	v_cvt_pk_bf16_f32 v153, v156, v157
	v_pk_add_f32 v[142:143], v[148:149], v[142:143]
	s_bitcmp1_b32 s21, 0
	v_add_f32_e32 v142, v142, v143
	v_add_f32_e32 v204, v158, v142
	v_cvt_pk_bf16_f32 v142, v2, v3
	v_add_u32_e32 v2, v166, v203
	v_cvt_pk_bf16_f32 v143, v144, v145
	v_cvt_pk_bf16_f32 v144, v146, v147
	v_cvt_pk_bf16_f32 v145, v148, v149
	ds_read_b128 v[146:149], v2 offset:8192
	ds_read_b128 v[234:237], v2 offset:10240
	ds_read_b128 v[226:229], v2 offset:12288
	ds_read_b128 v[212:215], v2 offset:14336
	s_waitcnt lgkmcnt(3)
	v_mfma_f32_16x16x32_bf16 v[114:117], v[146:149], v[150:153], v[114:117]
	s_cselect_b32 s0, 0x6000, 0
	s_add_i32 s0, s0, 0
	s_cmpk_eq_i32 s19, 0x10c0
	v_mfma_f32_16x16x32_bf16 v[110:113], v[146:149], v[142:145], v[110:113]
	ds_read_b128 v[146:149], v2 offset:16384
	s_waitcnt lgkmcnt(3)
	v_mfma_f32_16x16x32_bf16 v[106:109], v[234:237], v[150:153], v[106:109]
	v_mfma_f32_16x16x32_bf16 v[102:105], v[234:237], v[142:145], v[102:105]
	ds_read_b128 v[234:237], v2 offset:18432
	s_waitcnt lgkmcnt(3)
	v_mfma_f32_16x16x32_bf16 v[98:101], v[226:229], v[150:153], v[98:101]
	v_mfma_f32_16x16x32_bf16 v[94:97], v[226:229], v[142:145], v[94:97]
	ds_read_b128 v[226:229], v2 offset:20480
	s_waitcnt lgkmcnt(3)
	v_mfma_f32_16x16x32_bf16 v[90:93], v[212:215], v[150:153], v[90:93]
	v_mfma_f32_16x16x32_bf16 v[86:89], v[212:215], v[142:145], v[86:89]
	ds_read_b128 v[212:215], v2 offset:22528
	s_waitcnt lgkmcnt(3)
	v_mfma_f32_16x16x32_bf16 v[82:85], v[146:149], v[150:153], v[82:85]
	v_mfma_f32_16x16x32_bf16 v[78:81], v[146:149], v[142:145], v[78:81]
	s_waitcnt lgkmcnt(2)
	v_mfma_f32_16x16x32_bf16 v[74:77], v[234:237], v[150:153], v[74:77]
	v_mfma_f32_16x16x32_bf16 v[66:69], v[234:237], v[142:145], v[66:69]
	v_add_u32_e32 v2, s0, v210
	s_waitcnt vmcnt(5)
	ds_write_b128 v2, v[118:121]
	s_waitcnt vmcnt(4)
	ds_write_b128 v2, v[122:125] offset:4096
	s_waitcnt lgkmcnt(3)
	v_mfma_f32_16x16x32_bf16 v[70:73], v[226:229], v[150:153], v[70:73]
	v_mfma_f32_16x16x32_bf16 v[58:61], v[226:229], v[142:145], v[58:61]
	v_add3_u32 v2, s0, v208, v209
	s_waitcnt vmcnt(3)
	ds_write_b128 v2, v[126:129] offset:8192
	s_waitcnt vmcnt(1)
	ds_write_b128 v2, v[130:133] offset:12288
	s_waitcnt lgkmcnt(4)
	v_mfma_f32_16x16x32_bf16 v[62:65], v[212:215], v[150:153], v[62:65]
	s_waitcnt vmcnt(0)
	ds_write_b128 v2, v[134:137] offset:16384
	ds_write_b128 v2, v[138:141] offset:20480
	v_mfma_f32_16x16x32_bf16 v[54:57], v[212:215], v[142:145], v[54:57]
	s_cbranch_scc1 .LBB0_623
	s_mov_b32 s0, s21
	s_branch .LBB0_607
